# mixer-B FAST loop: back edge rotated (docs 7.11) - slot/counter SALU and DMA address math moved in front of the loop barrier, barrier becomes loop head
# baseline (speedup 1.0000x reference)
; template <int MODE, int NQ, int TS, bool FAST = false> ...
;     ...
;   const int lane = tid & 63, wave = tid >> 6, r32 = lane & 31, hh = lane >> 5;
;   constexpr float C2 = 0.125f * LOG2E;
;   constexpr int NS = 6;
;   bf16x8 qf[NQ][4];
; #pragma unroll
;   for (int nq = 0; nq < NQ; ++nq) { const bf16_t* qp = proj + (size_t)(seq_base + TS * (q0w + 32 * nq + r32)) * ld + qoff + hh * 8;
; #pragma unroll
;     for (int ks = 0; ks < 4; ++ks) qf[nq][ks] = *(const bf16x8*)(qp + ks * 16); }
;   f32x16 o[NQ][2];
;   float m2[NQ], l[NQ];
; #pragma unroll
;   for (int nq = 0; nq < NQ; ++nq) {
;     if (MODE == 0) {
;       const size_t tok = (size_t)(seq_base + q0w + 32 * nq + r32);
;       const bf16_t* po = part_o + tok * 512 + ooff + 4 * hh; const float* pm = part_ml + (tok * 8 + (ooff >> 6)) * 2;
;       m2[nq] = pm[0]; l[nq] = hh ? 0.f : pm[1];
; #pragma unroll
;       for (int g = 0; g < 4; ++g) { const uint2 a = *(const uint2*)(po + 8 * g), b = *(const uint2*)(po + 32 + 8 * g);
;         o[nq][0][4 * g] = bflo(a.x); o[nq][0][4 * g + 1] = bfhi(a.x); o[nq][0][4 * g + 2] = bflo(a.y); o[nq][0][4 * g + 3] = bfhi(a.y);
;         o[nq][1][4 * g] = bflo(b.x); o[nq][1][4 * g + 1] = bfhi(b.x); o[nq][1][4 * g + 2] = bflo(b.y); o[nq][1][4 * g + 3] = bfhi(b.y); }
;     } else {
;       m2[nq] = (MODE == 2) ? sink2 : -1e30f; l[nq] = 0.f;
; #pragma unroll
;       for (int r = 0; r < 16; ++r) { o[nq][0][r] = 0.f; o[nq][1][r] = 0.f; }
;     }
;   }
;   PG8_LAS unsigned char* L = (PG8_LAS unsigned char*)lds;
;   const int kkey_ = wave * 8 + (lane >> 3);
;   const bf16_t* kg = proj + (size_t)(seq_base + TS * kkey_) * ld + koff + (((lane & 7) ^ ((kkey_ >> 1) & 7)) * 8);
;   const bf16_t* vg = proj + (size_t)(seq_base + TS * ((wave & 3) * 16 + (lane >> 2))) * ld + voff + ((wave >> 2) * 4 + (lane & 3)) * 8;
;   const unsigned sdst = (unsigned)__builtin_amdgcn_readfirstlane(wave * 1024);
;     ...
;   const int ktl = kt1 - 1;
;   constexpr int TAB_OFF = 6 * 16384, TAB_N = (MODE == 3) ? 640 : 1024, TAB_ZERO = TAB_N / 2;
;   if (MODE == 0 || MODE == 3) {
;     float* tab = (float*)(lds + TAB_OFF);
;     for (int e = tid; e < TAB_N; e += 512) {
;       const int oo = e - TAB_ZERO, aa = oo < 0 ? -oo : oo;
;       if (MODE == 0) {
;         const int c = (aa <= 64 ? 1 : 0) + (((oo & 3) == 0 && aa <= 256) ? 1 : 0) + (((oo & 15) == 0 && aa <= 256) ? 1 : 0);
.LBB0_434:
	s_andn2_saveexec_b64 s[0:1], s[0:1]
	s_cbranch_execz .LBB0_364
	v_mov_b32_e32 v8, v222
	v_mov_b32_e32 v3, v1
	v_and_b32_e32 v9, 31, v8
	v_bfe_u32 v182, v8, 5, 1
	v_add_u32_e32 v168, v9, v37
	v_lshlrev_b32_e32 v2, 4, v182
	v_lshl_add_u64 v[2:3], v[38:39], 0, v[2:3]
	s_movk_i32 s4, 0x1200
	v_add_u32_e32 v166, 32, v168
	v_mad_i64_i32 v[4:5], s[8:9], v168, s4, v[2:3]
	v_mad_i64_i32 v[2:3], s[8:9], v166, s4, v[2:3]
	global_load_dwordx4 v[130:133], v[4:5], off offset:3072
	global_load_dwordx4 v[134:137], v[4:5], off offset:3104
	global_load_dwordx4 v[138:141], v[4:5], off offset:3136
	global_load_dwordx4 v[142:145], v[4:5], off offset:3168
	global_load_dwordx4 v[146:149], v[2:3], off offset:3072
	global_load_dwordx4 v[150:153], v[2:3], off offset:3104
	global_load_dwordx4 v[154:157], v[2:3], off offset:3136
	global_load_dwordx4 v[158:161], v[2:3], off offset:3168
	v_ashrrev_i32_e32 v10, 6, v8
	v_bfe_u32 v2, v8, 3, 3
	v_lshl_or_b32 v4, v10, 3, v2
	v_add_u32_e32 v5, s6, v4
	v_lshrrev_b32_e32 v4, 1, v4
	v_mov_b64_e32 v[2:3], s[66:67]
	v_xor_b32_e32 v4, v4, v8
	v_mad_i64_i32 v[2:3], s[8:9], v5, s4, v[2:3]
	s_lshl_b32 s76, s7, 1
	v_lshlrev_b32_e32 v4, 4, v4
	v_lshl_add_u64 v[2:3], v[2:3], 0, s[76:77]
	v_and_b32_e32 v4, 0x70, v4
	v_mov_b32_e32 v5, v1
	v_lshl_add_u64 v[2:3], v[2:3], 0, v[4:5]
	v_lshlrev_b32_e32 v4, 4, v10
	v_and_b32_e32 v4, 48, v4
	v_bfe_u32 v5, v8, 2, 4
	v_add3_u32 v4, v5, s6, v4
	v_and_b32_e32 v11, 3, v8
	s_mov_b32 s4, 0x1ffffffc
	v_mul_i32_i24_e32 v4, 0x900, v4
	v_mov_b32_e32 v5, v1
	v_and_or_b32 v6, v10, s4, v11
	v_lshl_add_u64 v[4:5], v[4:5], 1, s[66:67]
	v_lshlrev_b32_e32 v6, 3, v6
	v_readfirstlane_b32 s4, v10
	s_mov_b64 s[8:9], 0x1000
	v_lshl_add_u64 v[4:5], v[4:5], 0, s[76:77]
	v_ashrrev_i32_e32 v7, 31, v6
	s_lshl_b32 s4, s4, 10
	v_lshl_add_u64 v[172:173], v[2:3], 0, s[8:9]
	v_lshl_add_u64 v[4:5], v[6:7], 1, v[4:5]
	s_mov_b64 s[6:7], 0x1100
	s_mov_b32 m0, s4
	v_lshl_add_u64 v[174:175], v[4:5], 0, s[6:7]
	global_load_lds_dwordx4 v[172:173], off
	s_add_i32 m0, s4, 0x2000
	s_mov_b64 s[6:7], 0x49000
	global_load_lds_dwordx4 v[174:175], off
	v_lshl_add_u64 v[6:7], v[2:3], 0, s[6:7]
	s_add_i32 m0, s4, 0x4000
	s_mov_b64 s[6:7], 0x49100
	global_load_lds_dwordx4 v[6:7], off
	v_lshl_add_u64 v[6:7], v[4:5], 0, s[6:7]
	s_add_i32 m0, s4, 0x6000
	s_mov_b64 s[6:7], 0x91000
	global_load_lds_dwordx4 v[6:7], off
	v_lshl_add_u64 v[6:7], v[2:3], 0, s[6:7]
	s_add_i32 m0, s4, 0x8000
	s_mov_b64 s[6:7], 0x91100
	global_load_lds_dwordx4 v[6:7], off
	v_lshl_add_u64 v[6:7], v[4:5], 0, s[6:7]
	s_add_i32 m0, s4, 0xa000
	s_mov_b64 s[6:7], 0xd9000
	global_load_lds_dwordx4 v[6:7], off
	v_lshl_add_u64 v[2:3], v[2:3], 0, s[6:7]
	s_add_i32 m0, s4, 0xc000
	s_mov_b64 s[6:7], 0xd9100
	global_load_lds_dwordx4 v[2:3], off
	v_lshl_add_u64 v[2:3], v[4:5], 0, s[6:7]
	s_add_i32 m0, s4, 0xe000
	v_bfe_u32 v4, v8, 1, 3
	global_load_lds_dwordx4 v[2:3], off
	v_lshrrev_b32_e32 v3, 1, v8
	v_lshlrev_b32_e32 v2, 7, v9
	v_bitop3_b32 v3, v182, v3, 7 bitop3:0x78
	v_lshl_or_b32 v183, v3, 4, v2
	v_bitop3_b32 v3, v182, v4, 2 bitop3:0x36
	v_lshl_or_b32 v184, v3, 4, v2
	v_bitop3_b32 v3, v182, v4, 4 bitop3:0x36
	v_lshl_or_b32 v186, v3, 4, v2
	v_bitop3_b32 v3, v182, v4, 6 bitop3:0x36
	v_lshl_or_b32 v187, v3, 4, v2
	v_lshlrev_b32_e32 v2, 4, v8
	v_and_b32_e32 v2, 0xc0, v2
	v_lshlrev_b32_e32 v3, 1, v8
	s_waitcnt vmcnt(6) lgkmcnt(0)
	s_barrier
	v_lshl_or_b32 v2, v182, 8, v2
	v_and_b32_e32 v3, 32, v3
	v_lshlrev_b32_e32 v4, 3, v11
	v_mov_b32_e32 v50, v1
	v_mov_b32_e32 v51, v1
	v_or3_b32 v185, v2, v3, v4
	v_cmp_lt_i32_e32 vcc, 7, v10
	v_cmp_gt_i32_e64 s[38:39], 8, v10
	v_mov_b32_e32 v52, v1
	v_mov_b32_e32 v53, v1
	v_mov_b32_e32 v54, v1
	v_mov_b32_e32 v55, v1
	v_mov_b32_e32 v56, v1
	v_mov_b32_e32 v57, v1
	v_mov_b32_e32 v58, v1
	v_mov_b32_e32 v59, v1
	v_mov_b32_e32 v60, v1
	v_mov_b32_e32 v61, v1
	v_mov_b32_e32 v62, v1
	v_mov_b32_e32 v63, v1
	v_mov_b32_e32 v64, v1
	v_mov_b32_e32 v65, v1
	v_mov_b32_e32 v170, 0
	v_mov_b64_e32 v[34:35], v[50:51]
	v_mov_b64_e32 v[18:19], v[50:51]
	v_mov_b64_e32 v[2:3], v[50:51]
	s_movk_i32 s22, 0x1200
	v_ashrrev_i32_e32 v169, 31, v168
	v_ashrrev_i32_e32 v167, 31, v166
	s_add_i32 s6, s5, -1
	s_mov_b32 s12, 0
	v_mov_b64_e32 v[36:37], v[52:53]
	v_mov_b64_e32 v[38:39], v[54:55]
	v_mov_b64_e32 v[40:41], v[56:57]
	v_mov_b64_e32 v[42:43], v[58:59]
	v_mov_b64_e32 v[44:45], v[60:61]
	v_mov_b64_e32 v[46:47], v[62:63]
	v_mov_b64_e32 v[48:49], v[64:65]
	v_mov_b64_e32 v[20:21], v[52:53]
	v_mov_b64_e32 v[22:23], v[54:55]
	v_mov_b64_e32 v[24:25], v[56:57]
	v_mov_b64_e32 v[26:27], v[58:59]
	v_mov_b64_e32 v[28:29], v[60:61]
	v_mov_b64_e32 v[30:31], v[62:63]
	v_mov_b64_e32 v[32:33], v[64:65]
	v_mov_b64_e32 v[4:5], v[52:53]
	v_mov_b64_e32 v[6:7], v[54:55]
	v_mov_b64_e32 v[8:9], v[56:57]
	v_mov_b64_e32 v[10:11], v[58:59]
	v_mov_b64_e32 v[12:13], v[60:61]
	v_mov_b64_e32 v[14:15], v[62:63]
	v_mov_b64_e32 v[16:17], v[64:65]
	s_mov_b32 s9, 0
	s_mov_b32 s7, 0
	v_mov_b32_e32 v171, v170
	s_mov_b32 s8, s12
	s_add_i32 s12, s7, 4
	s_min_i32 s14, s12, s6
	s_cmp_gt_i32 s8, 1
	s_cselect_b32 s12, -2, 4
	s_add_i32 s15, s12, s8
	v_mad_i64_i32 v[248:249], s[12:13], s14, v237, v[172:173]
	v_mad_i64_i32 v[250:251], s[12:13], s14, v237, v[174:175]
	s_lshl_b32 s12, s15, 14
	s_add_i32 s15, s4, s12
	s_mov_b32 m0, s15
; template <int MODE, int NQ, int TS, bool FAST = false> ...
;     ...
;   auto QK = [&](int slot) {
;     const char* kb_ = lds + slot * 16384;
; #pragma unroll
;     for (int nq = 0; nq < NQ; ++nq)
; #pragma unroll
;       for (int r = 0; r < 16; ++r) { s[nq][0][r] = 0.f; s[nq][1][r] = 0.f; }
; #pragma unroll
;     for (int ks = 0; ks < 4; ++ks) {
;       const bf16x8 k0 = *(const bf16x8*)(kb_ + kfo4[ks]), k1 = *(const bf16x8*)(kb_ + kfo4[ks] + 4096);
; #pragma unroll
;       for (int nq = 0; nq < NQ; ++nq) { s[nq][0] = MFMA32(k0, qf[nq][ks], s[nq][0]); s[nq][1] = MFMA32(k1, qf[nq][ks], s[nq][1]); }
;     }
;   };
;   auto SM = [&](int kt) {
; #pragma unroll
;     for (int nq = 0; nq < NQ; ++nq) {
;       f32x16& s0 = s[nq][0]; f32x16& s1 = s[nq][1];
;       float mx = -1e30f;
;       if (MODE == 1) {
;       } else if (MODE == 0 || MODE == 3) {
;         const float* tb = (const float*)(lds + TAB_OFF) + (kt * 64 + 4 * hh - (q0w + 32 * nq + r32) + TAB_ZERO);
; #pragma unroll
;         for (int r = 0; r < 16; ++r) {
;           const float va = fmaf(s0[r], C2, tb[(r & 3) + 8 * (r >> 2)]), vb = fmaf(s1[r], C2, tb[(r & 3) + 8 * (r >> 2) + 32]);
;           s0[r] = va; s1[r] = vb; mx = fmaxf(mx, fmaxf(va, vb));
;         }
;       } else {
;         const float* tb = (const float*)(lds + TAB_OFF) + (wave & 3) * 512 + (kt * 64 + 4 * hh - (q0w + 32 * nq + r32) + 256);
; #pragma unroll
;         for (int r = 0; r < 16; ++r) {
;           const float va = fmaf(s0[r], C2, tb[(r & 3) + 8 * (r >> 2)]), vb = fmaf(s1[r], C2, tb[(r & 3) + 8 * (r >> 2) + 32]);
;           s0[r] = va; s1[r] = vb; mx = fmaxf(mx, fmaxf(va, vb));
;         }
;       }
;       float mn;
;       if (MODE == 1) {
;         mn = sink2;
;       } else {
;         if (__any(mx > m2[nq] + 8.f)) {
;           mx = fmaxf(mx, __shfl_xor(mx, 32));
;           mn = fmaxf(m2[nq], mx);
;           const float alpha = __builtin_amdgcn_exp2f(m2[nq] - mn);
;           l[nq] *= alpha;
; #pragma unroll
;           for (int r = 0; r < 16; ++r) { o[nq][0][r] *= alpha; o[nq][1][r] *= alpha; }
;           m2[nq] = mn;
;         }
;         mn = m2[nq];
;       }
;       float ls = 0.f;
; #pragma unroll
;       for (int r = 0; r < 16; ++r) {
;         float pa, pb;
;         if (MODE == 1) {
;           if (FAST) { pa = __builtin_amdgcn_exp2f(s0[r]); pb = __builtin_amdgcn_exp2f(s1[r]); }
.LBB0_436:
	s_waitcnt vmcnt(6) lgkmcnt(0)
	s_barrier
	global_load_lds_dwordx4 v[248:249], off
	s_add_i32 m0, s15, 0x2000
	s_nop 0
	global_load_lds_dwordx4 v[250:251], off
	s_and_saveexec_b64 s[12:13], s[38:39]
	s_xor_b64 s[26:27], exec, s[12:13]
	s_cbranch_execz .LBB0_438
	s_lshl_b32 s12, s8, 14
	v_or_b32_e32 v70, s12, v183
	ds_read_b128 v[66:69], v70
	ds_read_b128 v[82:85], v70 offset:4096
	v_or_b32_e32 v180, s12, v184
	ds_read_b128 v[176:179], v180
	ds_read_b128 v[188:191], v180 offset:4096
	v_or_b32_e32 v180, s12, v186
	s_waitcnt lgkmcnt(0)
	v_mfma_f32_32x32x16_bf16 v[98:113], v[66:69], v[130:133], 0
	v_mfma_f32_32x32x16_bf16 v[114:129], v[82:85], v[130:133], 0
	v_mfma_f32_32x32x16_bf16 v[82:97], v[82:85], v[146:149], 0
	v_mfma_f32_32x32x16_bf16 v[66:81], v[66:69], v[146:149], 0
	v_mfma_f32_32x32x16_bf16 v[82:97], v[188:191], v[150:153], v[82:97]
	v_mfma_f32_32x32x16_bf16 v[98:113], v[176:179], v[134:137], v[98:113]
	v_mfma_f32_32x32x16_bf16 v[114:129], v[188:191], v[134:137], v[114:129]
	v_mfma_f32_32x32x16_bf16 v[66:81], v[176:179], v[150:153], v[66:81]
	ds_read_b128 v[176:179], v180
	ds_read_b128 v[188:191], v180 offset:4096
	v_or_b32_e32 v180, s12, v187
	s_waitcnt lgkmcnt(0)
	v_mfma_f32_32x32x16_bf16 v[82:97], v[188:191], v[154:157], v[82:97]
	v_mfma_f32_32x32x16_bf16 v[98:113], v[176:179], v[138:141], v[98:113]
	v_mfma_f32_32x32x16_bf16 v[114:129], v[188:191], v[138:141], v[114:129]
	v_mfma_f32_32x32x16_bf16 v[66:81], v[176:179], v[154:157], v[66:81]
	ds_read_b128 v[176:179], v180
	ds_read_b128 v[188:191], v180 offset:4096
	s_waitcnt lgkmcnt(0)
	v_mfma_f32_32x32x16_bf16 v[82:97], v[188:191], v[158:161], v[82:97]
	v_mfma_f32_32x32x16_bf16 v[98:113], v[176:179], v[142:145], v[98:113]
	s_nop 10
	v_exp_f32_e32 v214, v92
	v_or_b32_e32 v92, s12, v185
	v_exp_f32_e32 v196, v86
	v_exp_f32_e32 v202, v88
	v_exp_f32_e32 v208, v90
	v_exp_f32_e32 v220, v94
	v_exp_f32_e32 v242, v96
	v_mfma_f32_32x32x16_bf16 v[114:129], v[188:191], v[142:145], v[114:129]
	v_exp_f32_e32 v181, v99
	v_exp_f32_e32 v189, v100
	v_exp_f32_e32 v193, v101
	v_exp_f32_e32 v195, v102
	v_exp_f32_e32 v199, v103
	v_exp_f32_e32 v201, v104
	v_exp_f32_e32 v205, v105
	v_mfma_f32_32x32x16_bf16 v[66:81], v[176:179], v[158:161], v[66:81]
	v_exp_f32_e32 v177, v98
	s_nop 2
	v_exp_f32_e32 v191, v116
	v_exp_f32_e32 v197, v118
	v_exp_f32_e32 v203, v120
	v_exp_f32_e32 v209, v122
	v_exp_f32_e32 v190, v84
	v_exp_f32_e32 v116, v85
	s_nop 1
	v_exp_f32_e32 v176, v66
	v_exp_f32_e32 v180, v67
	v_exp_f32_e32 v188, v68
	v_exp_f32_e32 v192, v69
	v_exp_f32_e32 v194, v70
	v_exp_f32_e32 v198, v71
	v_exp_f32_e32 v118, v87
	v_exp_f32_e32 v200, v72
	v_exp_f32_e32 v204, v73
	v_exp_f32_e32 v120, v89
	v_exp_f32_e32 v122, v91
	ds_read_b64_tr_b16 v[84:85], v92 offset:8192
	ds_read_b64_tr_b16 v[86:87], v92 offset:8704
	ds_read_b64_tr_b16 v[88:89], v92 offset:12288
	ds_read_b64_tr_b16 v[90:91], v92 offset:12800
	v_exp_f32_e32 v219, v110
	v_exp_f32_e32 v227, v111
	v_exp_f32_e32 v229, v112
	v_exp_f32_e32 v245, v113
	v_cvt_pk_bf16_f32 v110, v177, v181
	v_cvt_pk_bf16_f32 v111, v189, v193
	v_cvt_pk_bf16_f32 v112, v195, v199
	v_cvt_pk_bf16_f32 v113, v201, v205
	v_exp_f32_e32 v218, v78
	v_exp_f32_e32 v226, v79
	v_exp_f32_e32 v228, v80
	v_exp_f32_e32 v244, v81
	v_cvt_pk_bf16_f32 v78, v176, v180
	v_cvt_pk_bf16_f32 v79, v188, v192
	v_cvt_pk_bf16_f32 v80, v194, v198
	v_cvt_pk_bf16_f32 v81, v200, v204
	s_waitcnt lgkmcnt(0)
	v_mfma_f32_32x32x16_bf16 v[50:65], v[84:87], v[110:113], v[50:65]
	v_exp_f32_e32 v179, v114
	v_exp_f32_e32 v207, v106
	v_exp_f32_e32 v211, v107
	v_exp_f32_e32 v213, v108
	v_exp_f32_e32 v217, v109
	v_exp_f32_e32 v178, v82
	v_exp_f32_e32 v206, v74
	v_mfma_f32_32x32x16_bf16 v[34:49], v[88:91], v[110:113], v[34:49]
	v_exp_f32_e32 v210, v75
	v_exp_f32_e32 v212, v76
	v_exp_f32_e32 v216, v77
	v_exp_f32_e32 v115, v115
	v_exp_f32_e32 v114, v83
	v_exp_f32_e32 v117, v117
	v_cvt_pk_bf16_f32 v106, v207, v211
	v_mfma_f32_32x32x16_bf16 v[18:33], v[84:87], v[78:81], v[18:33]
	v_cvt_pk_bf16_f32 v107, v213, v217
	v_cvt_pk_bf16_f32 v108, v219, v227
	v_cvt_pk_bf16_f32 v109, v229, v245
	v_add_f32_e64 v66, v176, v178
	v_add_f32_e64 v67, v177, v179
	v_cvt_pk_bf16_f32 v74, v206, v210
	v_cvt_pk_bf16_f32 v75, v212, v216
	v_cvt_pk_bf16_f32 v76, v218, v226
	v_mfma_f32_32x32x16_bf16 v[2:17], v[88:91], v[78:81], v[2:17]
	ds_read_b64_tr_b16 v[84:85], v92 offset:9216
	ds_read_b64_tr_b16 v[86:87], v92 offset:9728
	ds_read_b64_tr_b16 v[88:89], v92 offset:13312
	ds_read_b64_tr_b16 v[90:91], v92 offset:13824
	v_cvt_pk_bf16_f32 v77, v228, v244
	v_exp_f32_e32 v119, v119
	v_pk_add_f32 v[66:67], v[66:67], 0 op_sel_hi:[1,0]
	v_pk_add_f32 v[68:69], v[180:181], v[114:115]
	v_exp_f32_e32 v121, v121
	v_pk_add_f32 v[66:67], v[68:69], v[66:67]
	s_waitcnt lgkmcnt(0)
; #define MFMA32(a, b, c) __builtin_amdgcn_mfma_f32_32x32x16_bf16((a), (b), (c), 0, 0, 0)
; DI unsigned pack2(float lo, float hi) { f32x2_t v = {lo, hi}; return __builtin_bit_cast(unsigned, __builtin_convertvector(v, bf16x2_t)); }
; DI s16x4 vtr(const char* p) { return __builtin_amdgcn_ds_read_tr16_b64_v4i16((lds_s16x4_ptr)p); }
; template <int MODE, int NQ, int TS, bool FAST = false> ...
;     ...
;       float ls = 0.f;
; #pragma unroll
;       for (int r = 0; r < 16; ++r) {
;         float pa, pb;
;         if (MODE == 1) {
;           if (FAST) { pa = __builtin_amdgcn_exp2f(s0[r]); pb = __builtin_amdgcn_exp2f(s1[r]); }
;           else { pa = __builtin_amdgcn_exp2f(s0[r] - mn); pb = __builtin_amdgcn_exp2f(s1[r] - mn); }
;         }
;         else { pa = __builtin_amdgcn_exp2f(s0[r] - mn); pb = __builtin_amdgcn_exp2f(s1[r] - mn); }
;         s0[r] = pa; s1[r] = pb; ls += pa + pb;
;       }
;       l[nq] += ls;
; #pragma unroll
;       for (int ks = 0; ks < 4; ++ks) {
;         uint4 t4;
;         const int rb = 8 * (ks & 1);
;         if (ks < 2) { t4.x = pack2(s0[rb], s0[rb + 1]); t4.y = pack2(s0[rb + 2], s0[rb + 3]); t4.z = pack2(s0[rb + 4], s0[rb + 5]); t4.w = pack2(s0[rb + 6], s0[rb + 7]); }
;         else { t4.x = pack2(s1[rb], s1[rb + 1]); t4.y = pack2(s1[rb + 2], s1[rb + 3]); t4.z = pack2(s1[rb + 4], s1[rb + 5]); t4.w = pack2(s1[rb + 6], s1[rb + 7]); }
;         pf[nq][ks] = __builtin_bit_cast(bf16x8, t4);
;       }
;     }
;   };
;   auto PV = [&](int slot) {
;     const char* vb_ = lds + slot * 16384 + vfo;
; #pragma unroll
;     for (int ks = 0; ks < 4; ++ks) {
;       const s16x4 a0 = vtr(vb_ + ks * 1024), a1 = vtr(vb_ + ks * 1024 + 512);
;       const s16x4 b0 = vtr(vb_ + 4096 + ks * 1024), b1 = vtr(vb_ + 4096 + ks * 1024 + 512);
;       const bf16x8 v0 = __builtin_shufflevector(a0, a1, 0, 1, 2, 3, 4, 5, 6, 7);
;       const bf16x8 v1 = __builtin_shufflevector(b0, b1, 0, 1, 2, 3, 4, 5, 6, 7);
; #pragma unroll
;       for (int nq = 0; nq < NQ; ++nq) { o[nq][0] = MFMA32(v0, pf[nq][ks], o[nq][0]); o[nq][1] = MFMA32(v1, pf[nq][ks], o[nq][1]); }
;     }
	v_mfma_f32_32x32x16_bf16 v[50:65], v[84:87], v[106:109], v[50:65]
	v_add_f32_e64 v68, v188, v190
	v_add_f32_e64 v69, v189, v191
	v_exp_f32_e32 v123, v123
	v_pk_add_f32 v[66:67], v[68:69], v[66:67]
	v_pk_add_f32 v[68:69], v[192:193], v[116:117]
	v_exp_f32_e32 v215, v124
	v_pk_add_f32 v[66:67], v[68:69], v[66:67]
	v_pk_add_f32 v[68:69], v[194:195], v[196:197]
	v_mfma_f32_32x32x16_bf16 v[34:49], v[88:91], v[106:109], v[34:49]
	v_add_f32_e64 v66, v68, v66
	v_add_f32_e64 v67, v69, v67
	v_add_f32_e64 v68, v198, v118
	v_add_f32_e64 v69, v199, v119
	v_exp_f32_e32 v125, v125
	v_pk_add_f32 v[66:67], v[68:69], v[66:67]
	v_pk_add_f32 v[68:69], v[200:201], v[202:203]
	v_exp_f32_e32 v124, v93
	v_pk_add_f32 v[66:67], v[68:69], v[66:67]
	v_mfma_f32_32x32x16_bf16 v[18:33], v[84:87], v[74:77], v[18:33]
	v_add_f32_e64 v68, v204, v120
	v_add_f32_e64 v69, v205, v121
	v_exp_f32_e32 v221, v126
	v_cvt_pk_bf16_f32 v102, v179, v115
	v_cvt_pk_bf16_f32 v103, v191, v117
	v_cvt_pk_bf16_f32 v104, v197, v119
	v_cvt_pk_bf16_f32 v105, v203, v121
	v_pk_add_f32 v[66:67], v[68:69], v[66:67]
	v_mfma_f32_32x32x16_bf16 v[2:17], v[88:91], v[74:77], v[2:17]
	ds_read_b64_tr_b16 v[84:85], v92 offset:10240
	ds_read_b64_tr_b16 v[86:87], v92 offset:10752
	ds_read_b64_tr_b16 v[88:89], v92 offset:14336
	ds_read_b64_tr_b16 v[90:91], v92 offset:14848
	v_add_f32_e64 v68, v206, v208
	v_add_f32_e64 v69, v207, v209
	v_cvt_pk_bf16_f32 v70, v178, v114
	v_cvt_pk_bf16_f32 v71, v190, v116
	v_cvt_pk_bf16_f32 v72, v196, v118
	v_cvt_pk_bf16_f32 v73, v202, v120
	v_exp_f32_e32 v127, v127
	v_exp_f32_e32 v126, v95
	v_pk_add_f32 v[66:67], v[68:69], v[66:67]
	v_pk_add_f32 v[68:69], v[210:211], v[122:123]
	s_waitcnt lgkmcnt(0)
	v_mfma_f32_32x32x16_bf16 v[50:65], v[84:87], v[102:105], v[50:65]
	v_exp_f32_e32 v243, v128
	v_pk_add_f32 v[66:67], v[68:69], v[66:67]
	v_pk_add_f32 v[68:69], v[212:213], v[214:215]
	v_exp_f32_e32 v129, v129
	v_exp_f32_e32 v128, v97
	v_pk_add_f32 v[66:67], v[68:69], v[66:67]
	v_pk_add_f32 v[68:69], v[216:217], v[124:125]
	v_mfma_f32_32x32x16_bf16 v[34:49], v[88:91], v[102:105], v[34:49]
	v_add_f32_e64 v66, v68, v66
	v_add_f32_e64 v67, v69, v67
	v_add_f32_e64 v68, v218, v220
	v_add_f32_e64 v69, v219, v221
	v_cvt_pk_bf16_f32 v98, v209, v123
	v_pk_add_f32 v[66:67], v[68:69], v[66:67]
	v_pk_add_f32 v[68:69], v[226:227], v[126:127]
	v_cvt_pk_bf16_f32 v99, v215, v125
	v_pk_add_f32 v[66:67], v[68:69], v[66:67]
	v_mfma_f32_32x32x16_bf16 v[18:33], v[84:87], v[70:73], v[18:33]
	v_add_f32_e64 v68, v228, v242
	v_add_f32_e64 v69, v229, v243
	v_cvt_pk_bf16_f32 v100, v221, v127
	v_add_f32_e64 v66, v68, v66
	v_add_f32_e64 v67, v69, v67
	v_pk_add_f32 v[68:69], v[244:245], v[128:129]
	v_cvt_pk_bf16_f32 v101, v243, v129
	v_pk_add_f32 v[82:83], v[68:69], v[66:67]
	v_cvt_pk_bf16_f32 v66, v208, v122
	v_mfma_f32_32x32x16_bf16 v[2:17], v[88:91], v[70:73], v[2:17]
	ds_read_b64_tr_b16 v[84:85], v92 offset:11264
	ds_read_b64_tr_b16 v[86:87], v92 offset:11776
	ds_read_b64_tr_b16 v[88:89], v92 offset:15360
	ds_read_b64_tr_b16 v[90:91], v92 offset:15872
	v_cvt_pk_bf16_f32 v67, v214, v124
	v_cvt_pk_bf16_f32 v68, v220, v126
	v_cvt_pk_bf16_f32 v69, v242, v128
	s_waitcnt lgkmcnt(0)
	v_mfma_f32_32x32x16_bf16 v[50:65], v[84:87], v[98:101], v[50:65]
	v_mfma_f32_32x32x16_bf16 v[34:49], v[88:91], v[98:101], v[34:49]
	v_mfma_f32_32x32x16_bf16 v[18:33], v[84:87], v[66:69], v[18:33]
	v_mfma_f32_32x32x16_bf16 v[2:17], v[88:91], v[66:69], v[2:17]

; #define ATT_ISSUE(tile, slot) do { const size_t go_ = (size_t)(tile) * 64 * TS * ld; \
;     __builtin_amdgcn_global_load_lds((const unsigned*)(kg + go_), (PG8_LAS unsigned*)(L + (slot) * 16384 + sdst), 16, 0, 0); \
;     __builtin_amdgcn_global_load_lds((const unsigned*)(vg + go_), (PG8_LAS unsigned*)(L + (slot) * 16384 + 8192 + sdst), 16, 0, 0); } while (0)
; template <int MODE, int NQ, int TS, bool FAST = false> ...
;     ...
;   for (int kt = kt0; kt < kt1; ++kt) {
;     { const int tn = (kt + 4 < ktl) ? kt + 4 : ktl; int s4 = slot + 4; if (s4 >= NS) s4 -= NS; ATT_ISSUE(tn, s4); }
;     const bool act = tile_active(kt);
;     if (!g2) {
;       if (act) { QK(slot); SM(kt); PV(slot); }
;     } else {
;       if (kt > kt0 && tile_active(kt - 1)) PV(sp);
;       if (act) { QK(slot); SM(kt); }
;     }
;     asm volatile("s_waitcnt vmcnt(6) lgkmcnt(0)\n\ts_barrier" ::: "memory");
;     sp = slot; slot = (slot + 1 == NS) ? 0 : slot + 1;
;   }
;   if (g2 && tile_active(ktl)) PV(sp);
;   asm volatile("s_waitcnt vmcnt(0)\n\ts_barrier" ::: "memory");
.LBB0_442:
	s_or_b64 exec, exec, s[26:27]
	v_pk_add_f32 v[170:171], v[170:171], v[82:83]
	s_add_i32 s9, s8, 1
	s_cmp_lg_u32 s9, 6
	s_cselect_b32 s12, s9, 0
	s_add_i32 s7, s7, 1
	s_cmp_eq_u32 s5, s7
	s_cbranch_scc1 .Lbrot_exit
	s_mov_b32 s9, s8
	s_mov_b32 s8, s12
	s_add_i32 s12, s7, 4
	s_min_i32 s14, s12, s6
	s_cmp_gt_i32 s8, 1
	s_cselect_b32 s12, -2, 4
	s_add_i32 s15, s12, s8
	v_mad_i64_i32 v[248:249], s[12:13], s14, v237, v[172:173]
	v_mad_i64_i32 v[250:251], s[12:13], s14, v237, v[174:175]
	s_lshl_b32 s12, s15, 14
	s_add_i32 s15, s4, s12
	s_mov_b32 m0, s15
	s_branch .LBB0_436
.Lbrot_exit:
	s_waitcnt vmcnt(6) lgkmcnt(0)
	s_barrier
